# sgu staging loads issued together per K-step instead of one-at-a-time; fb_sample loop rewritten with 8 loads in flight
# baseline (speedup 1.0000x reference)
.LBB0_169:
	v_ashrrev_i32_e32 v0, 3, v143
	v_lshrrev_b32_e32 v1, 29, v0
	v_add_lshl_u32 v1, v0, v1, 3
	v_and_b32_e32 v1, 0xffffffc0, v1
	v_and_b32_e32 v2, 56, v183
	v_and_b32_e32 v0, 7, v0
	v_or3_b32 v160, v1, v2, v0
	s_mov_b32 s0, 0x2aaaaaab
	v_mul_hi_i32 v0, v160, s0
	v_lshrrev_b32_e32 v1, 31, v0
	v_ashrrev_i32_e32 v0, 5, v0
	v_ashrrev_i32_e32 v161, 31, v160
	v_add_u32_e32 v184, v0, v1
	v_lshlrev_b64 v[0:1], 8, v[160:161]
	v_or_b32_e32 v4, v0, v144
	v_mov_b32_e32 v5, v1
	v_lshlrev_b64 v[4:5], 8, v[4:5]
	v_lshl_add_u64 v[162:163], v[146:147], 0, v[4:5]
	v_or_b32_e32 v4, v0, v148
	v_mov_b32_e32 v5, v1
	v_lshlrev_b64 v[4:5], 8, v[4:5]
	v_lshlrev_b32_e32 v2, 14, v184
	v_lshl_add_u64 v[164:165], v[146:147], 0, v[4:5]
	v_or_b32_e32 v4, v0, v150
	v_or_b32_e32 v0, v0, v152
	v_ashrrev_i32_e32 v3, 31, v2
	v_mov_b32_e32 v5, v1
	v_lshlrev_b64 v[0:1], 8, v[0:1]
	v_lshl_add_u64 v[170:171], v[146:147], 0, v[0:1]
	v_lshl_add_u64 v[168:169], v[2:3], 1, v[154:155]
	v_lshlrev_b64 v[4:5], 8, v[4:5]
	v_lshl_add_u64 v[166:167], v[146:147], 0, v[4:5]
	s_movk_i32 s0, 0x4000
	v_add_co_u32_e32 v172, vcc, s0, v168
	s_movk_i32 s0, 0xc0
	s_nop 0
	v_addc_co_u32_e32 v173, vcc, 0, v169, vcc
	global_load_dwordx4 v[218:221], v[162:163], off
	global_load_dwordx4 v[222:225], v[164:165], off
	global_load_dwordx4 v[226:229], v[166:167], off
	global_load_dwordx4 v[238:241], v[170:171], off
	global_load_dwordx4 v[244:247], v[168:169], off
	global_load_dwordx4 v[248:251], v[172:173], off
	v_mul_lo_u32 v130, v184, s0
	v_sub_u32_e32 v130, v160, v130
	v_lshl_or_b32 v130, v130, 8, v145
	v_ashrrev_i32_e32 v130, 7, v130
	v_ashrrev_i32_e32 v131, 31, v130
	v_lshlrev_b64 v[130:131], 7, v[130:131]
	v_add_u32_e32 v143, s23, v143
	s_movk_i32 s0, 0x2ff
	v_cmp_lt_i32_e32 vcc, s0, v143
	v_add_u32_e32 v183, s20, v183
	s_or_b64 s[8:9], vcc, s[8:9]
	s_waitcnt vmcnt(0)
	ds_write_b128 v149, v[218:221]
	ds_write_b128 v151, v[222:225]
	ds_write_b128 v153, v[226:229]
	ds_write_b128 v157, v[238:241]
	ds_write_b128 v159, v[244:247]
	ds_write_b128 v174, v[248:251]
	s_waitcnt lgkmcnt(0)
	s_barrier
	global_load_dwordx4 v[218:221], v[162:163], off offset:64
	global_load_dwordx4 v[222:225], v[164:165], off offset:64
	global_load_dwordx4 v[226:229], v[166:167], off offset:64
	global_load_dwordx4 v[238:241], v[170:171], off offset:64
	global_load_dwordx4 v[244:247], v[168:169], off offset:64
	global_load_dwordx4 v[248:251], v[172:173], off offset:64
	ds_read_b128 v[0:3], v175 offset:2560
	ds_read_b128 v[4:7], v175 offset:5120
	ds_read_b128 v[8:11], v175 offset:7680
	ds_read_b128 v[12:15], v176 offset:23040
	ds_read_b128 v[16:19], v175
	ds_read_b128 v[186:189], v175 offset:32
	ds_read_b128 v[64:67], v176 offset:20480
	ds_read_b128 v[190:193], v176 offset:20512
	s_waitcnt lgkmcnt(1)
	v_mfma_f32_32x32x16_bf16 v[112:127], v[16:19], v[64:67], 0
	ds_read_b128 v[194:197], v175 offset:2592
	ds_read_b128 v[198:201], v175 offset:5152
	ds_read_b128 v[202:205], v175 offset:7712
	ds_read_b128 v[206:209], v176 offset:23072
	v_mfma_f32_32x32x16_bf16 v[48:63], v[16:19], v[12:15], 0
	s_waitcnt lgkmcnt(4)
	v_mfma_f32_32x32x16_bf16 v[112:127], v[186:189], v[190:193], v[112:127]
	s_waitcnt lgkmcnt(0)
	v_mfma_f32_32x32x16_bf16 v[48:63], v[186:189], v[206:209], v[48:63]
	v_mfma_f32_32x32x16_bf16 v[96:111], v[0:3], v[64:67], 0
	v_mfma_f32_32x32x16_bf16 v[32:47], v[0:3], v[12:15], 0
	v_mfma_f32_32x32x16_bf16 v[80:95], v[4:7], v[64:67], 0
	v_mfma_f32_32x32x16_bf16 v[16:31], v[4:7], v[12:15], 0
	v_mfma_f32_32x32x16_bf16 v[64:79], v[8:11], v[64:67], 0
	s_waitcnt vmcnt(0)
	ds_write_b128 v177, v[218:221]
	ds_write_b128 v178, v[222:225]
	ds_write_b128 v179, v[226:229]
	ds_write_b128 v180, v[238:241]
	ds_write_b128 v181, v[244:247]
	ds_write_b128 v182, v[248:251]
	v_mfma_f32_32x32x16_bf16 v[0:15], v[8:11], v[12:15], 0
	s_waitcnt lgkmcnt(0)
	s_barrier
	global_load_dwordx4 v[218:221], v[162:163], off offset:128
	global_load_dwordx4 v[222:225], v[164:165], off offset:128
	global_load_dwordx4 v[226:229], v[166:167], off offset:128
	global_load_dwordx4 v[238:241], v[170:171], off offset:128
	global_load_dwordx4 v[244:247], v[168:169], off offset:128
	global_load_dwordx4 v[248:251], v[172:173], off offset:128
	v_mfma_f32_32x32x16_bf16 v[96:111], v[194:197], v[190:193], v[96:111]
	v_mfma_f32_32x32x16_bf16 v[32:47], v[194:197], v[206:209], v[32:47]
	v_mfma_f32_32x32x16_bf16 v[80:95], v[198:201], v[190:193], v[80:95]
	v_mfma_f32_32x32x16_bf16 v[16:31], v[198:201], v[206:209], v[16:31]
	v_mfma_f32_32x32x16_bf16 v[64:79], v[202:205], v[190:193], v[64:79]
	v_mfma_f32_32x32x16_bf16 v[0:15], v[202:205], v[206:209], v[0:15]
	ds_read_b128 v[186:189], v175 offset:33280
	ds_read_b128 v[190:193], v175 offset:35840
	ds_read_b128 v[194:197], v175 offset:38400
	ds_read_b128 v[198:201], v176 offset:53760
	ds_read_b128 v[202:205], v175 offset:30720
	ds_read_b128 v[206:209], v175 offset:30752
	ds_read_b128 v[210:213], v176 offset:51200
	ds_read_b128 v[214:217], v176 offset:51232
	s_waitcnt lgkmcnt(1)
	v_mfma_f32_32x32x16_bf16 v[96:111], v[186:189], v[210:213], v[96:111]
	v_mfma_f32_32x32x16_bf16 v[32:47], v[186:189], v[198:201], v[32:47]
	v_mfma_f32_32x32x16_bf16 v[48:63], v[202:205], v[198:201], v[48:63]
	v_mfma_f32_32x32x16_bf16 v[80:95], v[190:193], v[210:213], v[80:95]
	v_mfma_f32_32x32x16_bf16 v[16:31], v[190:193], v[198:201], v[16:31]
	v_mfma_f32_32x32x16_bf16 v[64:79], v[194:197], v[210:213], v[64:79]
	v_mfma_f32_32x32x16_bf16 v[0:15], v[194:197], v[198:201], v[0:15]
	ds_read_b128 v[186:189], v175 offset:33312
	ds_read_b128 v[190:193], v175 offset:35872
	ds_read_b128 v[194:197], v175 offset:38432
	ds_read_b128 v[198:201], v176 offset:53792
	s_waitcnt lgkmcnt(3)
	v_mfma_f32_32x32x16_bf16 v[96:111], v[186:189], v[214:217], v[96:111]
	s_waitcnt lgkmcnt(0)
	v_mfma_f32_32x32x16_bf16 v[32:47], v[186:189], v[198:201], v[32:47]
	v_mfma_f32_32x32x16_bf16 v[112:127], v[202:205], v[210:213], v[112:127]
	v_mfma_f32_32x32x16_bf16 v[48:63], v[206:209], v[198:201], v[48:63]
	v_mfma_f32_32x32x16_bf16 v[80:95], v[190:193], v[214:217], v[80:95]
	v_mfma_f32_32x32x16_bf16 v[16:31], v[190:193], v[198:201], v[16:31]
	v_mfma_f32_32x32x16_bf16 v[64:79], v[194:197], v[214:217], v[64:79]
	s_waitcnt vmcnt(0)
	ds_write_b128 v149, v[218:221]
	ds_write_b128 v151, v[222:225]
	ds_write_b128 v153, v[226:229]
	ds_write_b128 v157, v[238:241]
	ds_write_b128 v159, v[244:247]
	ds_write_b128 v174, v[248:251]
	v_mfma_f32_32x32x16_bf16 v[0:15], v[194:197], v[198:201], v[0:15]
	s_waitcnt lgkmcnt(0)
	s_barrier
	global_load_dwordx4 v[218:221], v[162:163], off offset:192
	global_load_dwordx4 v[222:225], v[164:165], off offset:192
	global_load_dwordx4 v[226:229], v[166:167], off offset:192
	global_load_dwordx4 v[238:241], v[170:171], off offset:192
	global_load_dwordx4 v[244:247], v[168:169], off offset:192
	global_load_dwordx4 v[248:251], v[172:173], off offset:192
	v_mfma_f32_32x32x16_bf16 v[112:127], v[206:209], v[214:217], v[112:127]
	ds_read_b128 v[186:189], v175 offset:2560
	ds_read_b128 v[190:193], v175 offset:5120
	ds_read_b128 v[194:197], v175 offset:7680
	ds_read_b128 v[198:201], v176 offset:23040
	ds_read_b128 v[202:205], v175
	ds_read_b128 v[206:209], v175 offset:32
	ds_read_b128 v[210:213], v176 offset:20480
	ds_read_b128 v[214:217], v176 offset:20512
	s_waitcnt lgkmcnt(1)
	v_mfma_f32_32x32x16_bf16 v[96:111], v[186:189], v[210:213], v[96:111]
	v_mfma_f32_32x32x16_bf16 v[32:47], v[186:189], v[198:201], v[32:47]
	v_mfma_f32_32x32x16_bf16 v[48:63], v[202:205], v[198:201], v[48:63]
	v_mfma_f32_32x32x16_bf16 v[80:95], v[190:193], v[210:213], v[80:95]
	v_mfma_f32_32x32x16_bf16 v[16:31], v[190:193], v[198:201], v[16:31]
	v_mfma_f32_32x32x16_bf16 v[64:79], v[194:197], v[210:213], v[64:79]
	v_mfma_f32_32x32x16_bf16 v[0:15], v[194:197], v[198:201], v[0:15]
	ds_read_b128 v[186:189], v175 offset:2592
	ds_read_b128 v[190:193], v175 offset:5152
	ds_read_b128 v[194:197], v175 offset:7712
	ds_read_b128 v[198:201], v176 offset:23072
	s_waitcnt lgkmcnt(3)
	v_mfma_f32_32x32x16_bf16 v[96:111], v[186:189], v[214:217], v[96:111]
	s_waitcnt lgkmcnt(0)
	v_mfma_f32_32x32x16_bf16 v[32:47], v[186:189], v[198:201], v[32:47]
	v_mfma_f32_32x32x16_bf16 v[48:63], v[206:209], v[198:201], v[48:63]
	v_mfma_f32_32x32x16_bf16 v[80:95], v[190:193], v[214:217], v[80:95]
	v_mfma_f32_32x32x16_bf16 v[16:31], v[190:193], v[198:201], v[16:31]
	v_mfma_f32_32x32x16_bf16 v[64:79], v[194:197], v[214:217], v[64:79]
	v_mfma_f32_32x32x16_bf16 v[0:15], v[194:197], v[198:201], v[0:15]
	s_waitcnt vmcnt(0)
	ds_write_b128 v177, v[218:221]
	ds_write_b128 v178, v[222:225]
	ds_write_b128 v179, v[226:229]
	ds_write_b128 v180, v[238:241]
	ds_write_b128 v181, v[244:247]
	ds_write_b128 v182, v[248:251]
	v_mfma_f32_32x32x16_bf16 v[112:127], v[202:205], v[210:213], v[112:127]
	s_waitcnt lgkmcnt(0)
	s_barrier
	ds_read_b128 v[162:165], v175 offset:33280
	ds_read_b128 v[166:169], v175 offset:35840
	ds_read_b128 v[170:173], v175 offset:38400
	ds_read_b128 v[186:189], v176 offset:53760
	ds_read_b128 v[190:193], v175 offset:30720
	ds_read_b128 v[194:197], v175 offset:30752
	ds_read_b128 v[198:201], v176 offset:51200
	ds_read_b128 v[202:205], v176 offset:51232
	s_waitcnt lgkmcnt(1)
	v_mfma_f32_32x32x16_bf16 v[96:111], v[162:165], v[198:201], v[96:111]
	v_mfma_f32_32x32x16_bf16 v[32:47], v[162:165], v[186:189], v[32:47]
	v_mfma_f32_32x32x16_bf16 v[48:63], v[190:193], v[186:189], v[48:63]
	v_mfma_f32_32x32x16_bf16 v[80:95], v[166:169], v[198:201], v[80:95]
	v_mfma_f32_32x32x16_bf16 v[16:31], v[166:169], v[186:189], v[16:31]
	v_mfma_f32_32x32x16_bf16 v[64:79], v[170:173], v[198:201], v[64:79]
	v_mfma_f32_32x32x16_bf16 v[0:15], v[170:173], v[186:189], v[0:15]
	ds_read_b128 v[162:165], v175 offset:33312
	ds_read_b128 v[166:169], v175 offset:35872
	ds_read_b128 v[170:173], v175 offset:38432
	ds_read_b128 v[186:189], v176 offset:53792
	s_waitcnt lgkmcnt(0)
	s_barrier
	v_mfma_f32_32x32x16_bf16 v[96:111], v[162:165], v[202:205], v[96:111]
	v_mfma_f32_32x32x16_bf16 v[32:47], v[162:165], v[186:189], v[32:47]
	v_lshlrev_b32_e32 v162, 7, v184
	v_ashrrev_i32_e32 v163, 31, v162
	v_lshlrev_b64 v[132:133], 1, v[162:163]
	v_or_b32_e32 v164, v130, v156
	v_mov_b32_e32 v165, v131
	v_lshl_add_u64 v[134:135], s[94:95], 0, v[132:133]
	v_or_b32_e32 v136, v162, v156
	v_mfma_f32_32x32x16_bf16 v[80:95], v[166:169], v[202:205], v[80:95]
	v_ashrrev_i32_e32 v137, 31, v136
	v_lshl_add_u64 v[160:161], v[136:137], 2, s[76:77]
	global_load_dword v160, v[160:161], off
	v_lshl_add_u64 v[132:133], s[6:7], 0, v[132:133]
	v_or_b32_e32 v130, v130, v158
	v_mov_b32_e32 v137, v163
	s_waitcnt vmcnt(0)
	v_pk_add_f32 v[96:97], v[96:97], v[160:161] op_sel_hi:[1,0]
	v_mfma_f32_32x32x16_bf16 v[16:31], v[166:169], v[186:189], v[16:31]
	v_lshlrev_b64 v[166:167], 12, v[164:165]
	v_lshl_add_u64 v[166:167], v[134:135], 0, v[166:167]
	v_lshl_add_u64 v[166:167], v[166:167], 0, v[128:129]
	global_load_dwordx2 v[168:169], v[166:167], off
	v_lshlrev_b64 v[164:165], 11, v[164:165]
	v_lshl_add_u64 v[164:165], v[132:133], 0, v[164:165]
	v_pk_add_f32 v[98:99], v[98:99], v[160:161] op_sel_hi:[1,0]
	v_mfma_f32_32x32x16_bf16 v[112:127], v[206:209], v[214:217], v[112:127]
	v_add_f32_e64 v100, v100, v160
	v_add_f32_e64 v101, v101, v160
	v_add_f32_e64 v80, v80, v160
	v_add_f32_e64 v81, v81, v160
	v_add_f32_e64 v82, v82, v160
	v_add_f32_e64 v83, v83, v160
	v_pk_add_f32 v[84:85], v[84:85], v[160:161] op_sel_hi:[1,0]
	v_mfma_f32_32x32x16_bf16 v[112:127], v[190:193], v[198:201], v[112:127]
	v_mfma_f32_32x32x16_bf16 v[112:127], v[194:197], v[202:205], v[112:127]
	v_mfma_f32_32x32x16_bf16 v[64:79], v[170:173], v[202:205], v[64:79]
	s_nop 10
	v_add_f32_e64 v112, v112, v160
	v_add_f32_e64 v113, v113, v160
	v_add_f32_e64 v114, v114, v160
	v_add_f32_e64 v115, v115, v160
	v_add_f32_e64 v116, v116, v160
	v_add_f32_e64 v117, v117, v160
	v_pk_add_f32 v[118:119], v[118:119], v[160:161] op_sel_hi:[1,0]
	v_mfma_f32_32x32x16_bf16 v[0:15], v[170:173], v[186:189], v[0:15]
	v_add_f32_e64 v64, v64, v160
	v_add_f32_e64 v65, v65, v160
	v_add_f32_e64 v66, v66, v160
	v_add_f32_e64 v67, v67, v160
	v_add_f32_e64 v68, v68, v160
	v_add_f32_e64 v69, v69, v160
	s_waitcnt vmcnt(0)
	v_lshlrev_b32_e32 v170, 16, v168
	v_and_b32_e32 v171, 0xffff0000, v168
	v_lshlrev_b32_e32 v168, 16, v169
	v_and_b32_e32 v169, 0xffff0000, v169
	v_pk_mul_f32 v[112:113], v[112:113], v[170:171]
	v_pk_mul_f32 v[114:115], v[114:115], v[168:169]
	v_cvt_pk_bf16_f32 v112, v112, v113
	v_cvt_pk_bf16_f32 v113, v114, v115
	v_lshl_add_u64 v[114:115], v[164:165], 0, v[128:129]
	global_store_dwordx2 v[114:115], v[112:113], off
	global_load_dwordx2 v[112:113], v[166:167], off offset:16
	v_mfma_f32_32x32x16_bf16 v[48:63], v[194:197], v[186:189], v[48:63]
	s_waitcnt vmcnt(0)
	v_lshlrev_b32_e32 v164, 16, v112
	v_and_b32_e32 v165, 0xffff0000, v112
	v_lshlrev_b32_e32 v112, 16, v113
	v_and_b32_e32 v113, 0xffff0000, v113
	v_pk_mul_f32 v[116:117], v[116:117], v[164:165]
	v_pk_mul_f32 v[112:113], v[118:119], v[112:113]
	v_cvt_pk_bf16_f32 v116, v116, v117
	v_cvt_pk_bf16_f32 v117, v112, v113
	global_load_dwordx2 v[112:113], v[166:167], off offset:32
	v_pk_add_f32 v[118:119], v[120:121], v[160:161] op_sel_hi:[1,0]
	global_store_dwordx2 v[114:115], v[116:117], off offset:16
	s_waitcnt vmcnt(1)
	v_lshlrev_b32_e32 v116, 16, v112
	v_and_b32_e32 v117, 0xffff0000, v112
	v_pk_mul_f32 v[116:117], v[118:119], v[116:117]
	v_lshlrev_b32_e32 v112, 16, v113
	v_and_b32_e32 v113, 0xffff0000, v113
	v_pk_add_f32 v[118:119], v[122:123], v[160:161] op_sel_hi:[1,0]
	v_cvt_pk_bf16_f32 v116, v116, v117
	v_pk_mul_f32 v[112:113], v[118:119], v[112:113]
	v_pk_add_f32 v[118:119], v[124:125], v[160:161] op_sel_hi:[1,0]
	v_cvt_pk_bf16_f32 v117, v112, v113
	global_load_dwordx2 v[112:113], v[166:167], off offset:48
	s_nop 0
	global_store_dwordx2 v[114:115], v[116:117], off offset:32
	s_waitcnt vmcnt(1)
	v_lshlrev_b32_e32 v116, 16, v112
	v_and_b32_e32 v117, 0xffff0000, v112
	v_pk_mul_f32 v[116:117], v[118:119], v[116:117]
	v_lshlrev_b32_e32 v112, 16, v113
	v_and_b32_e32 v113, 0xffff0000, v113
	v_pk_add_f32 v[118:119], v[126:127], v[160:161] op_sel_hi:[1,0]
	v_cvt_pk_bf16_f32 v116, v116, v117
	v_pk_mul_f32 v[112:113], v[118:119], v[112:113]
	s_nop 0
	v_cvt_pk_bf16_f32 v117, v112, v113
	global_load_dwordx2 v[112:113], v[166:167], off offset:64
	s_nop 0
	global_store_dwordx2 v[114:115], v[116:117], off offset:48
	s_waitcnt vmcnt(1)
	v_lshlrev_b32_e32 v116, 16, v112
	v_and_b32_e32 v117, 0xffff0000, v112
	v_lshlrev_b32_e32 v112, 16, v113
	v_and_b32_e32 v113, 0xffff0000, v113
	v_pk_mul_f32 v[96:97], v[96:97], v[116:117]
	v_pk_mul_f32 v[98:99], v[98:99], v[112:113]
	v_cvt_pk_bf16_f32 v96, v96, v97
	v_cvt_pk_bf16_f32 v97, v98, v99
	global_store_dwordx2 v[114:115], v[96:97], off offset:64
	global_load_dwordx2 v[96:97], v[166:167], off offset:80
	s_waitcnt vmcnt(0)
	v_lshlrev_b32_e32 v98, 16, v96
	v_and_b32_e32 v99, 0xffff0000, v96
	v_pk_mul_f32 v[98:99], v[100:101], v[98:99]
	v_lshlrev_b32_e32 v96, 16, v97
	v_and_b32_e32 v97, 0xffff0000, v97
	v_pk_add_f32 v[100:101], v[102:103], v[160:161] op_sel_hi:[1,0]
	v_cvt_pk_bf16_f32 v98, v98, v99
	v_pk_mul_f32 v[96:97], v[100:101], v[96:97]
	v_pk_add_f32 v[100:101], v[104:105], v[160:161] op_sel_hi:[1,0]
	v_cvt_pk_bf16_f32 v99, v96, v97
	global_load_dwordx2 v[96:97], v[166:167], off offset:96
	s_nop 0
	global_store_dwordx2 v[114:115], v[98:99], off offset:80
	s_waitcnt vmcnt(1)
	v_lshlrev_b32_e32 v98, 16, v96
	v_and_b32_e32 v99, 0xffff0000, v96
	v_pk_mul_f32 v[98:99], v[100:101], v[98:99]
	v_lshlrev_b32_e32 v96, 16, v97
	v_and_b32_e32 v97, 0xffff0000, v97
	v_pk_add_f32 v[100:101], v[106:107], v[160:161] op_sel_hi:[1,0]
	v_cvt_pk_bf16_f32 v98, v98, v99
	v_pk_mul_f32 v[96:97], v[100:101], v[96:97]
	v_pk_add_f32 v[100:101], v[108:109], v[160:161] op_sel_hi:[1,0]
	v_cvt_pk_bf16_f32 v99, v96, v97
	global_load_dwordx2 v[96:97], v[166:167], off offset:112
	s_nop 0
	global_store_dwordx2 v[114:115], v[98:99], off offset:96
	s_waitcnt vmcnt(1)
	v_lshlrev_b32_e32 v98, 16, v96
	v_and_b32_e32 v99, 0xffff0000, v96
	v_pk_mul_f32 v[98:99], v[100:101], v[98:99]
	v_lshlrev_b32_e32 v96, 16, v97
	v_and_b32_e32 v97, 0xffff0000, v97
	v_pk_add_f32 v[100:101], v[110:111], v[160:161] op_sel_hi:[1,0]
	v_cvt_pk_bf16_f32 v98, v98, v99
	v_pk_mul_f32 v[96:97], v[100:101], v[96:97]
	s_nop 0
	v_cvt_pk_bf16_f32 v99, v96, v97
	global_load_dwordx2 v[96:97], v[166:167], off offset:128
	s_nop 0
	global_store_dwordx2 v[114:115], v[98:99], off offset:112
	s_waitcnt vmcnt(1)
	v_lshlrev_b32_e32 v98, 16, v96
	v_and_b32_e32 v99, 0xffff0000, v96
	v_lshlrev_b32_e32 v96, 16, v97
	v_and_b32_e32 v97, 0xffff0000, v97
	v_pk_mul_f32 v[80:81], v[80:81], v[98:99]
	v_pk_mul_f32 v[82:83], v[82:83], v[96:97]
	v_cvt_pk_bf16_f32 v80, v80, v81
	v_cvt_pk_bf16_f32 v81, v82, v83
	global_store_dwordx2 v[114:115], v[80:81], off offset:128
	global_load_dwordx2 v[80:81], v[166:167], off offset:144
	s_waitcnt vmcnt(0)
	v_lshlrev_b32_e32 v82, 16, v80
	v_and_b32_e32 v83, 0xffff0000, v80
	v_pk_mul_f32 v[82:83], v[84:85], v[82:83]
	v_lshlrev_b32_e32 v80, 16, v81
	v_and_b32_e32 v81, 0xffff0000, v81
	v_pk_add_f32 v[84:85], v[86:87], v[160:161] op_sel_hi:[1,0]
	v_cvt_pk_bf16_f32 v82, v82, v83
	v_pk_mul_f32 v[80:81], v[84:85], v[80:81]
	v_pk_add_f32 v[84:85], v[88:89], v[160:161] op_sel_hi:[1,0]
	v_cvt_pk_bf16_f32 v83, v80, v81
	global_load_dwordx2 v[80:81], v[166:167], off offset:160
	s_nop 0
	global_store_dwordx2 v[114:115], v[82:83], off offset:144
	s_waitcnt vmcnt(1)
	v_lshlrev_b32_e32 v82, 16, v80
	v_and_b32_e32 v83, 0xffff0000, v80
	v_pk_mul_f32 v[82:83], v[84:85], v[82:83]
	v_lshlrev_b32_e32 v80, 16, v81
	v_and_b32_e32 v81, 0xffff0000, v81
	v_pk_add_f32 v[84:85], v[90:91], v[160:161] op_sel_hi:[1,0]
	v_cvt_pk_bf16_f32 v82, v82, v83
	v_pk_mul_f32 v[80:81], v[84:85], v[80:81]
	v_pk_add_f32 v[84:85], v[92:93], v[160:161] op_sel_hi:[1,0]
	v_cvt_pk_bf16_f32 v83, v80, v81
	global_load_dwordx2 v[80:81], v[166:167], off offset:176
	s_nop 0
	global_store_dwordx2 v[114:115], v[82:83], off offset:160
	s_waitcnt vmcnt(1)
	v_lshlrev_b32_e32 v82, 16, v80
	v_and_b32_e32 v83, 0xffff0000, v80
	v_pk_mul_f32 v[82:83], v[84:85], v[82:83]
	v_lshlrev_b32_e32 v80, 16, v81
	v_and_b32_e32 v81, 0xffff0000, v81
	v_pk_add_f32 v[84:85], v[94:95], v[160:161] op_sel_hi:[1,0]
	v_cvt_pk_bf16_f32 v82, v82, v83
	v_pk_mul_f32 v[80:81], v[84:85], v[80:81]
	s_nop 0
	v_cvt_pk_bf16_f32 v83, v80, v81
	global_load_dwordx2 v[80:81], v[166:167], off offset:192
	s_nop 0
	global_store_dwordx2 v[114:115], v[82:83], off offset:176
	s_waitcnt vmcnt(1)
	v_lshlrev_b32_e32 v82, 16, v80
	v_and_b32_e32 v83, 0xffff0000, v80
	v_lshlrev_b32_e32 v80, 16, v81
	v_and_b32_e32 v81, 0xffff0000, v81
	v_pk_mul_f32 v[64:65], v[64:65], v[82:83]
	v_pk_mul_f32 v[66:67], v[66:67], v[80:81]
	v_cvt_pk_bf16_f32 v64, v64, v65
	v_cvt_pk_bf16_f32 v65, v66, v67
	global_store_dwordx2 v[114:115], v[64:65], off offset:192
	global_load_dwordx2 v[64:65], v[166:167], off offset:208
	s_waitcnt vmcnt(0)
	v_lshlrev_b32_e32 v66, 16, v64
	v_and_b32_e32 v67, 0xffff0000, v64
	v_pk_mul_f32 v[66:67], v[68:69], v[66:67]
	v_lshlrev_b32_e32 v64, 16, v65
	v_and_b32_e32 v65, 0xffff0000, v65
	v_pk_add_f32 v[68:69], v[70:71], v[160:161] op_sel_hi:[1,0]
	v_cvt_pk_bf16_f32 v66, v66, v67
	v_pk_mul_f32 v[64:65], v[68:69], v[64:65]
	v_pk_add_f32 v[68:69], v[72:73], v[160:161] op_sel_hi:[1,0]
	v_cvt_pk_bf16_f32 v67, v64, v65
	global_load_dwordx2 v[64:65], v[166:167], off offset:224
	s_nop 0
	global_store_dwordx2 v[114:115], v[66:67], off offset:208
	s_waitcnt vmcnt(1)
	v_lshlrev_b32_e32 v66, 16, v64
	v_and_b32_e32 v67, 0xffff0000, v64
	v_pk_mul_f32 v[66:67], v[68:69], v[66:67]
	v_lshlrev_b32_e32 v64, 16, v65
	v_and_b32_e32 v65, 0xffff0000, v65
	v_pk_add_f32 v[68:69], v[74:75], v[160:161] op_sel_hi:[1,0]
	v_cvt_pk_bf16_f32 v66, v66, v67
	v_pk_mul_f32 v[64:65], v[68:69], v[64:65]
	v_pk_add_f32 v[68:69], v[76:77], v[160:161] op_sel_hi:[1,0]
	v_cvt_pk_bf16_f32 v67, v64, v65
	global_load_dwordx2 v[64:65], v[166:167], off offset:240
	s_nop 0
	global_store_dwordx2 v[114:115], v[66:67], off offset:224
	s_waitcnt vmcnt(1)
	v_lshlrev_b32_e32 v66, 16, v64
	v_and_b32_e32 v67, 0xffff0000, v64
	v_pk_mul_f32 v[66:67], v[68:69], v[66:67]
	v_lshlrev_b32_e32 v64, 16, v65
	v_and_b32_e32 v65, 0xffff0000, v65
	v_pk_add_f32 v[68:69], v[78:79], v[160:161] op_sel_hi:[1,0]
	v_cvt_pk_bf16_f32 v66, v66, v67
	v_pk_mul_f32 v[64:65], v[68:69], v[64:65]
	v_lshlrev_b64 v[68:69], 11, v[130:131]
	v_cvt_pk_bf16_f32 v67, v64, v65
	global_store_dwordx2 v[114:115], v[66:67], off offset:240
	v_lshlrev_b64 v[66:67], 12, v[130:131]
	v_lshl_add_u64 v[66:67], v[134:135], 0, v[66:67]
	v_lshl_add_u64 v[64:65], v[136:137], 2, s[76:77]
	v_lshl_add_u64 v[66:67], v[66:67], 0, v[128:129]
	global_load_dword v64, v[64:65], off offset:128
	v_lshl_add_u64 v[68:69], v[132:133], 0, v[68:69]
	global_load_dwordx2 v[70:71], v[66:67], off
	s_waitcnt vmcnt(1)
	v_pk_add_f32 v[48:49], v[48:49], v[64:65] op_sel_hi:[1,0]
	v_pk_add_f32 v[50:51], v[50:51], v[64:65] op_sel_hi:[1,0]
	s_waitcnt vmcnt(0)
	v_lshlrev_b32_e32 v72, 16, v70
	v_and_b32_e32 v73, 0xffff0000, v70
	v_lshlrev_b32_e32 v70, 16, v71
	v_and_b32_e32 v71, 0xffff0000, v71
	v_pk_mul_f32 v[48:49], v[48:49], v[72:73]
	v_pk_mul_f32 v[50:51], v[50:51], v[70:71]
	v_cvt_pk_bf16_f32 v48, v48, v49
	v_cvt_pk_bf16_f32 v49, v50, v51
	v_lshl_add_u64 v[50:51], v[68:69], 0, v[128:129]
	global_store_dwordx2 v[50:51], v[48:49], off
	global_load_dwordx2 v[48:49], v[66:67], off offset:16
	v_pk_add_f32 v[52:53], v[52:53], v[64:65] op_sel_hi:[1,0]
	v_pk_add_f32 v[54:55], v[54:55], v[64:65] op_sel_hi:[1,0]
	v_pk_add_f32 v[32:33], v[32:33], v[64:65] op_sel_hi:[1,0]
	v_pk_add_f32 v[34:35], v[34:35], v[64:65] op_sel_hi:[1,0]
	v_pk_add_f32 v[36:37], v[36:37], v[64:65] op_sel_hi:[1,0]
	v_pk_add_f32 v[16:17], v[16:17], v[64:65] op_sel_hi:[1,0]
	v_pk_add_f32 v[18:19], v[18:19], v[64:65] op_sel_hi:[1,0]
	v_pk_add_f32 v[20:21], v[20:21], v[64:65] op_sel_hi:[1,0]
	v_pk_add_f32 v[0:1], v[0:1], v[64:65] op_sel_hi:[1,0]
	v_pk_add_f32 v[2:3], v[2:3], v[64:65] op_sel_hi:[1,0]
	v_pk_add_f32 v[4:5], v[4:5], v[64:65] op_sel_hi:[1,0]
	s_waitcnt vmcnt(0)
	v_lshlrev_b32_e32 v68, 16, v48
	v_and_b32_e32 v69, 0xffff0000, v48
	v_lshlrev_b32_e32 v48, 16, v49
	v_and_b32_e32 v49, 0xffff0000, v49
	v_pk_mul_f32 v[52:53], v[52:53], v[68:69]
	v_pk_mul_f32 v[48:49], v[54:55], v[48:49]
	v_cvt_pk_bf16_f32 v52, v52, v53
	v_cvt_pk_bf16_f32 v53, v48, v49
	global_load_dwordx2 v[48:49], v[66:67], off offset:32
	v_pk_add_f32 v[54:55], v[56:57], v[64:65] op_sel_hi:[1,0]
	global_store_dwordx2 v[50:51], v[52:53], off offset:16
	s_waitcnt vmcnt(1)
	v_lshlrev_b32_e32 v52, 16, v48
	v_and_b32_e32 v53, 0xffff0000, v48
	v_pk_mul_f32 v[52:53], v[54:55], v[52:53]
	v_lshlrev_b32_e32 v48, 16, v49
	v_and_b32_e32 v49, 0xffff0000, v49
	v_pk_add_f32 v[54:55], v[58:59], v[64:65] op_sel_hi:[1,0]
	v_cvt_pk_bf16_f32 v52, v52, v53
	v_pk_mul_f32 v[48:49], v[54:55], v[48:49]
	v_pk_add_f32 v[54:55], v[60:61], v[64:65] op_sel_hi:[1,0]
	v_cvt_pk_bf16_f32 v53, v48, v49
	global_load_dwordx2 v[48:49], v[66:67], off offset:48
	s_nop 0
	global_store_dwordx2 v[50:51], v[52:53], off offset:32
	s_waitcnt vmcnt(1)
	v_lshlrev_b32_e32 v52, 16, v48
	v_and_b32_e32 v53, 0xffff0000, v48
	v_pk_mul_f32 v[52:53], v[54:55], v[52:53]
	v_lshlrev_b32_e32 v48, 16, v49
	v_and_b32_e32 v49, 0xffff0000, v49
	v_pk_add_f32 v[54:55], v[62:63], v[64:65] op_sel_hi:[1,0]
	v_cvt_pk_bf16_f32 v52, v52, v53
	v_pk_mul_f32 v[48:49], v[54:55], v[48:49]
	s_nop 0
	v_cvt_pk_bf16_f32 v53, v48, v49
	global_load_dwordx2 v[48:49], v[66:67], off offset:64
	s_nop 0
	global_store_dwordx2 v[50:51], v[52:53], off offset:48
	s_waitcnt vmcnt(1)
	v_lshlrev_b32_e32 v52, 16, v48
	v_and_b32_e32 v53, 0xffff0000, v48
	v_lshlrev_b32_e32 v48, 16, v49
	v_and_b32_e32 v49, 0xffff0000, v49
	v_pk_mul_f32 v[32:33], v[32:33], v[52:53]
	v_pk_mul_f32 v[34:35], v[34:35], v[48:49]
	v_cvt_pk_bf16_f32 v32, v32, v33
	v_cvt_pk_bf16_f32 v33, v34, v35
	global_store_dwordx2 v[50:51], v[32:33], off offset:64
	global_load_dwordx2 v[32:33], v[66:67], off offset:80
	s_waitcnt vmcnt(0)
	v_lshlrev_b32_e32 v34, 16, v32
	v_and_b32_e32 v35, 0xffff0000, v32
	v_pk_mul_f32 v[34:35], v[36:37], v[34:35]
	v_lshlrev_b32_e32 v32, 16, v33
	v_and_b32_e32 v33, 0xffff0000, v33
	v_pk_add_f32 v[36:37], v[38:39], v[64:65] op_sel_hi:[1,0]
	v_cvt_pk_bf16_f32 v34, v34, v35
	v_pk_mul_f32 v[32:33], v[36:37], v[32:33]
	v_pk_add_f32 v[36:37], v[40:41], v[64:65] op_sel_hi:[1,0]
	v_cvt_pk_bf16_f32 v35, v32, v33
	global_load_dwordx2 v[32:33], v[66:67], off offset:96
	s_nop 0
	global_store_dwordx2 v[50:51], v[34:35], off offset:80
	s_waitcnt vmcnt(1)
	v_lshlrev_b32_e32 v34, 16, v32
	v_and_b32_e32 v35, 0xffff0000, v32
	v_pk_mul_f32 v[34:35], v[36:37], v[34:35]
	v_lshlrev_b32_e32 v32, 16, v33
	v_and_b32_e32 v33, 0xffff0000, v33
	v_pk_add_f32 v[36:37], v[42:43], v[64:65] op_sel_hi:[1,0]
	v_cvt_pk_bf16_f32 v34, v34, v35
	v_pk_mul_f32 v[32:33], v[36:37], v[32:33]
	v_pk_add_f32 v[36:37], v[44:45], v[64:65] op_sel_hi:[1,0]
	v_cvt_pk_bf16_f32 v35, v32, v33
	global_load_dwordx2 v[32:33], v[66:67], off offset:112
	s_nop 0
	global_store_dwordx2 v[50:51], v[34:35], off offset:96
	s_waitcnt vmcnt(1)
	v_lshlrev_b32_e32 v34, 16, v32
	v_and_b32_e32 v35, 0xffff0000, v32
	v_pk_mul_f32 v[34:35], v[36:37], v[34:35]
	v_lshlrev_b32_e32 v32, 16, v33
	v_and_b32_e32 v33, 0xffff0000, v33
	v_pk_add_f32 v[36:37], v[46:47], v[64:65] op_sel_hi:[1,0]
	v_cvt_pk_bf16_f32 v34, v34, v35
	v_pk_mul_f32 v[32:33], v[36:37], v[32:33]
	s_nop 0
	v_cvt_pk_bf16_f32 v35, v32, v33
	global_load_dwordx2 v[32:33], v[66:67], off offset:128
	s_nop 0
	global_store_dwordx2 v[50:51], v[34:35], off offset:112
	s_waitcnt vmcnt(1)
	v_lshlrev_b32_e32 v34, 16, v32
	v_and_b32_e32 v35, 0xffff0000, v32
	v_lshlrev_b32_e32 v32, 16, v33
	v_and_b32_e32 v33, 0xffff0000, v33
	v_pk_mul_f32 v[16:17], v[16:17], v[34:35]
	v_pk_mul_f32 v[18:19], v[18:19], v[32:33]
	v_cvt_pk_bf16_f32 v16, v16, v17
	v_cvt_pk_bf16_f32 v17, v18, v19
	global_store_dwordx2 v[50:51], v[16:17], off offset:128
	global_load_dwordx2 v[16:17], v[66:67], off offset:144
	s_waitcnt vmcnt(0)
	v_lshlrev_b32_e32 v18, 16, v16
	v_and_b32_e32 v19, 0xffff0000, v16
	v_pk_mul_f32 v[18:19], v[20:21], v[18:19]
	v_lshlrev_b32_e32 v16, 16, v17
	v_and_b32_e32 v17, 0xffff0000, v17
	v_pk_add_f32 v[20:21], v[22:23], v[64:65] op_sel_hi:[1,0]
	v_cvt_pk_bf16_f32 v18, v18, v19
	v_pk_mul_f32 v[16:17], v[20:21], v[16:17]
	v_pk_add_f32 v[20:21], v[24:25], v[64:65] op_sel_hi:[1,0]
	v_cvt_pk_bf16_f32 v19, v16, v17
	global_load_dwordx2 v[16:17], v[66:67], off offset:160
	s_nop 0
	global_store_dwordx2 v[50:51], v[18:19], off offset:144
	s_waitcnt vmcnt(1)
	v_lshlrev_b32_e32 v18, 16, v16
	v_and_b32_e32 v19, 0xffff0000, v16
	v_pk_mul_f32 v[18:19], v[20:21], v[18:19]
	v_lshlrev_b32_e32 v16, 16, v17
	v_and_b32_e32 v17, 0xffff0000, v17
	v_pk_add_f32 v[20:21], v[26:27], v[64:65] op_sel_hi:[1,0]
	v_cvt_pk_bf16_f32 v18, v18, v19
	v_pk_mul_f32 v[16:17], v[20:21], v[16:17]
	v_pk_add_f32 v[20:21], v[28:29], v[64:65] op_sel_hi:[1,0]
	v_cvt_pk_bf16_f32 v19, v16, v17
	global_load_dwordx2 v[16:17], v[66:67], off offset:176
	s_nop 0
	global_store_dwordx2 v[50:51], v[18:19], off offset:160
	s_waitcnt vmcnt(1)
	v_lshlrev_b32_e32 v18, 16, v16
	v_and_b32_e32 v19, 0xffff0000, v16
	v_pk_mul_f32 v[18:19], v[20:21], v[18:19]
	v_lshlrev_b32_e32 v16, 16, v17
	v_and_b32_e32 v17, 0xffff0000, v17
	v_pk_add_f32 v[20:21], v[30:31], v[64:65] op_sel_hi:[1,0]
	v_cvt_pk_bf16_f32 v18, v18, v19
	v_pk_mul_f32 v[16:17], v[20:21], v[16:17]
	s_nop 0
	v_cvt_pk_bf16_f32 v19, v16, v17
	global_load_dwordx2 v[16:17], v[66:67], off offset:192
	s_nop 0
	global_store_dwordx2 v[50:51], v[18:19], off offset:176
	s_waitcnt vmcnt(1)
	v_lshlrev_b32_e32 v18, 16, v16
	v_and_b32_e32 v19, 0xffff0000, v16
	v_lshlrev_b32_e32 v16, 16, v17
	v_and_b32_e32 v17, 0xffff0000, v17
	v_pk_mul_f32 v[0:1], v[0:1], v[18:19]
	v_pk_mul_f32 v[2:3], v[2:3], v[16:17]
	v_cvt_pk_bf16_f32 v0, v0, v1
	v_cvt_pk_bf16_f32 v1, v2, v3
	global_store_dwordx2 v[50:51], v[0:1], off offset:192
	global_load_dwordx2 v[0:1], v[66:67], off offset:208
	s_waitcnt vmcnt(0)
	v_lshlrev_b32_e32 v2, 16, v0
	v_and_b32_e32 v3, 0xffff0000, v0
	v_pk_mul_f32 v[2:3], v[4:5], v[2:3]
	v_lshlrev_b32_e32 v0, 16, v1
	v_and_b32_e32 v1, 0xffff0000, v1
	v_pk_add_f32 v[4:5], v[6:7], v[64:65] op_sel_hi:[1,0]
	v_cvt_pk_bf16_f32 v2, v2, v3
	v_pk_mul_f32 v[0:1], v[4:5], v[0:1]
	v_pk_add_f32 v[4:5], v[8:9], v[64:65] op_sel_hi:[1,0]
	v_cvt_pk_bf16_f32 v3, v0, v1
	global_load_dwordx2 v[0:1], v[66:67], off offset:224
	s_nop 0
	global_store_dwordx2 v[50:51], v[2:3], off offset:208
	s_waitcnt vmcnt(1)
	v_lshlrev_b32_e32 v2, 16, v0
	v_and_b32_e32 v3, 0xffff0000, v0
	v_pk_mul_f32 v[2:3], v[4:5], v[2:3]
	v_lshlrev_b32_e32 v0, 16, v1
	v_and_b32_e32 v1, 0xffff0000, v1
	v_pk_add_f32 v[4:5], v[10:11], v[64:65] op_sel_hi:[1,0]
	v_cvt_pk_bf16_f32 v2, v2, v3
	v_pk_mul_f32 v[0:1], v[4:5], v[0:1]
	v_pk_add_f32 v[4:5], v[12:13], v[64:65] op_sel_hi:[1,0]
	v_cvt_pk_bf16_f32 v3, v0, v1
	global_load_dwordx2 v[0:1], v[66:67], off offset:240
	s_nop 0
	global_store_dwordx2 v[50:51], v[2:3], off offset:224
	s_waitcnt vmcnt(1)
	v_lshlrev_b32_e32 v2, 16, v0
	v_and_b32_e32 v3, 0xffff0000, v0
	v_pk_mul_f32 v[2:3], v[4:5], v[2:3]
	v_lshlrev_b32_e32 v0, 16, v1
	v_and_b32_e32 v1, 0xffff0000, v1
	v_pk_add_f32 v[4:5], v[14:15], v[64:65] op_sel_hi:[1,0]
	v_cvt_pk_bf16_f32 v2, v2, v3
	v_pk_mul_f32 v[0:1], v[4:5], v[0:1]
	s_nop 0
	v_cvt_pk_bf16_f32 v3, v0, v1
	global_store_dwordx2 v[50:51], v[2:3], off offset:240
	s_andn2_b64 exec, exec, s[8:9]
	s_cbranch_execnz .LBB0_169
	s_nop 0
	s_nop 0
	s_nop 0
	s_nop 0
	s_nop 0
	s_nop 0
	s_nop 0
	s_nop 0
	s_nop 0
	s_nop 0
	s_nop 0
	s_nop 0
	s_nop 0
	s_nop 0
	s_nop 0
	s_nop 0
	s_nop 0
	s_nop 0
	s_nop 0
	s_nop 0
